# in-proj GEMM: tile index uses bid^0x80 so the 24 tail tiles land on CUs whose fk_compute items (sample set) finish early
# speedup vs baseline: 1.0020x; 1.0020x over previous
;     __host__ __device__ bool next(int i, Unit& u) const {
;         const long L = (long)i * G + c; if (L >= nwg) return false;
;         u.ks = 0;
;         if (KS > 1) { const int l = (int)L; u.ks = l % KS; const int t = l / KS; u.pm = t % nM; u.pn = t / nM; return true; }
;         int wgid = (int)L; { const int q = nwg / NXCD, r = nwg % NXCD, xcd = wgid % NXCD, off = wgid / NXCD; wgid = (xcd < r ? xcd * (q + 1) : r * (q + 1) + (xcd - r) * q) + off; }
;         const int nig = WGM * nN, gid = wgid / nig, fm = gid * WGM, gsz = (nM - fm) < WGM ? (nM - fm) : WGM;
;         u.pm = fm + ((wgid % nig) % gsz); u.pn = (wgid % nig) / gsz; return true;
.LBB0_993:
	s_xor_b32 s27, s27, 0x80
	v_mov_b32_e32 v8, v202
	s_cmpk_lt_i32 s27, 0x1218
	s_cselect_b64 s[2:3], -1, 0
	s_cmpk_gt_i32 s27, 0x1217
	v_readfirstlane_b32 s8, v8
	s_cbranch_scc1 .LBB0_995
	s_ashr_i32 s4, s27, 31
	s_lshr_b32 s4, s4, 29
	s_add_i32 s4, s27, s4
	s_ashr_i32 s5, s4, 3
	s_and_b32 s4, s4, -8
	s_sub_i32 s4, s27, s4
	s_cmp_lt_i32 s4, 0
	s_movk_i32 s9, 0x244
	s_cselect_b32 s9, s9, 0x243
	s_mul_i32 s4, s4, s9
	s_add_i32 s4, s4, s5
	s_mul_hi_i32 s5, s4, 0x2aaaaaab
	s_lshr_b32 s9, s5, 31
	s_ashr_i32 s5, s5, 4
	s_add_i32 s5, s5, s9
	s_lshl_b32 s9, s5, 3
	s_sub_i32 s10, 0x182, s9
	s_min_u32 s10, s10, 8
	s_mulk_i32 s5, 0x60
	s_sub_i32 s11, s4, s5
	v_cvt_f32_ubyte0_e32 v1, s10
	v_cvt_f32_i32_e32 v0, s11
	v_rcp_iflag_f32_e32 v2, v1
	s_ashr_i32 s4, s11, 30
	s_or_b32 s12, s4, 1
	v_mul_f32_e32 v2, v0, v2
	v_trunc_f32_e32 v2, v2
	v_fma_f32 v0, -v2, v1, v0
	v_cvt_i32_f32_e32 v2, v2
	v_cmp_ge_f32_e64 s[4:5], |v0|, v1
	s_and_b64 s[4:5], s[4:5], exec
	s_cselect_b32 s4, s12, 0
	v_readfirstlane_b32 s5, v2
	s_add_i32 s4, s5, s4
	s_sext_i32_i8 s18, s4
	s_mul_i32 s4, s4, s10
	s_sub_i32 s4, s11, s4
	s_sext_i32_i8 s4, s4
	s_add_i32 s16, s9, s4
